# dsa_post: the three per-row loads (latent c, indexer key, indexer weight) issued together at the top of the row iteration with counted waits
# baseline (speedup 1.0000x reference)
.LBB0_809:
	v_readlane_b32 s4, v253, 4
	v_readlane_b32 s5, v253, 5
	s_nop 1
	v_lshl_add_u64 v[24:25], v[12:13], 0, s[4:5]
	v_lshl_add_u64 v[40:41], v[14:15], 0, s[4:5]
	v_lshl_add_u64 v[42:43], v[16:17], 0, s[4:5]
	global_load_dwordx2 v[24:25], v[24:25], off
	global_load_dword v40, v[40:41], off
	global_load_ushort v42, v[42:43], off
	s_waitcnt vmcnt(2)
	v_and_b32_e32 v27, 0xffff0000, v25
	v_and_b32_e32 v29, 0xffff0000, v24
	v_lshlrev_b32_e32 v26, 16, v25
	v_lshlrev_b32_e32 v28, 16, v24
	v_mov_b32_e32 v30, v29
	v_mov_b32_e32 v31, v27
	v_mov_b32_e32 v24, v28
	v_mov_b32_e32 v25, v26
	v_pk_mul_f32 v[30:31], v[30:31], v[30:31]
	s_nop 0
	v_pk_fma_f32 v[24:25], v[24:25], v[24:25], v[30:31]
	s_nop 0
	v_add_f32_e32 v24, v24, v25
	s_nop 1
	v_add_f32_dpp v24, v24, v24 quad_perm:[1,0,3,2] row_mask:0xf bank_mask:0xf
	s_nop 1
	v_add_f32_dpp v24, v24, v24 quad_perm:[2,3,0,1] row_mask:0xf bank_mask:0xf
	s_nop 1
	v_add_f32_dpp v24, v24, v24 row_half_mirror row_mask:0xf bank_mask:0xf
	s_nop 1
	v_add_f32_dpp v24, v24, v24 row_mirror row_mask:0xf bank_mask:0xf
	v_mov_b32_e32 v25, v24
	s_nop 1
	v_permlane16_swap_b32 v25, v24
	v_add_f32_e32 v24, v24, v25
	v_mov_b32_e32 v25, v24
	s_nop 1
	v_permlane32_swap_b32 v25, v24
	v_add_f32_e32 v24, v24, v25
	v_fmamk_f32 v24, v24, 0x3b800000, v167
	v_cmp_gt_f32_e32 vcc, s54, v24
	v_mul_f32_e32 v25, 0x4f800000, v24
	s_nop 0
	v_cndmask_b32_e32 v24, v24, v25, vcc
	v_sqrt_f32_e32 v25, v24
	s_nop 0
	v_add_u32_e32 v30, -1, v25
	v_fma_f32 v31, -v30, v25, v24
	v_cmp_ge_f32_e64 s[0:1], 0, v31
	v_add_u32_e32 v31, 1, v25
	s_nop 0
	v_cndmask_b32_e64 v30, v25, v30, s[0:1]
	v_fma_f32 v25, -v31, v25, v24
	v_cmp_lt_f32_e64 s[0:1], 0, v25
	s_nop 1
	v_cndmask_b32_e64 v25, v30, v31, s[0:1]
	v_mul_f32_e32 v30, 0x37800000, v25
	v_cndmask_b32_e32 v25, v25, v30, vcc
	v_cmp_class_f32_e32 vcc, v24, v171
	s_nop 1
	v_cndmask_b32_e32 v24, v25, v24, vcc
	v_div_scale_f32 v25, s[0:1], v24, v24, 1.0
	v_rcp_f32_e32 v30, v25
	s_nop 0
	v_fma_f32 v31, -v25, v30, 1.0
	v_fmac_f32_e32 v30, v31, v30
	v_div_scale_f32 v31, vcc, 1.0, v24, 1.0
	v_mul_f32_e32 v33, v31, v30
	v_fma_f32 v34, -v25, v33, v31
	v_fmac_f32_e32 v33, v34, v30
	v_fma_f32 v25, -v25, v33, v31
	v_div_fmas_f32 v25, v25, v30, v33
	v_div_fixup_f32 v24, v25, v24, 1.0
	v_pk_mul_f32 v[28:29], v[24:25], v[28:29] op_sel_hi:[0,1]
	v_pk_mul_f32 v[24:25], v[24:25], v[26:27] op_sel_hi:[0,1]
	v_pk_mul_f32 v[28:29], v[0:1], v[28:29]
	v_pk_mul_f32 v[24:25], v[2:3], v[24:25]
	v_cvt_pk_bf16_f32 v28, v28, v29
	v_cvt_pk_bf16_f32 v29, v24, v25
	v_lshl_add_u64 v[24:25], v[10:11], 0, s[4:5]
	global_store_dwordx2 v[24:25], v[28:29], off
	s_waitcnt vmcnt(2)
	v_lshlrev_b32_e32 v24, 16, v40
	v_and_b32_e32 v25, 0xffff0000, v40
	v_pk_mul_f32 v[26:27], v[24:25], v[24:25]
	s_nop 0
	v_add_f32_e32 v26, v26, v27
	s_nop 1
	v_add_f32_dpp v26, v26, v26 quad_perm:[1,0,3,2] row_mask:0xf bank_mask:0xf
	s_nop 1
	v_add_f32_dpp v26, v26, v26 quad_perm:[2,3,0,1] row_mask:0xf bank_mask:0xf
	s_nop 1
	v_add_f32_dpp v26, v26, v26 row_half_mirror row_mask:0xf bank_mask:0xf
	s_nop 1
	v_add_f32_dpp v26, v26, v26 row_mirror row_mask:0xf bank_mask:0xf
	v_mov_b32_e32 v27, v26
	s_nop 1
	v_permlane16_swap_b32 v27, v26
	v_add_f32_e32 v26, v26, v27
	v_mov_b32_e32 v27, v26
	s_nop 1
	v_permlane32_swap_b32 v27, v26
	v_add_f32_e32 v26, v26, v27
	v_fmamk_f32 v26, v26, 0x3c000000, v167
	v_cmp_gt_f32_e32 vcc, s54, v26
	v_mul_f32_e32 v27, 0x4f800000, v26
	s_nop 0
	v_cndmask_b32_e32 v26, v26, v27, vcc
	v_sqrt_f32_e32 v27, v26
	s_nop 0
	v_add_u32_e32 v28, -1, v27
	v_fma_f32 v29, -v28, v27, v26
	v_cmp_ge_f32_e64 s[0:1], 0, v29
	v_add_u32_e32 v29, 1, v27
	s_nop 0
	v_cndmask_b32_e64 v28, v27, v28, s[0:1]
	v_fma_f32 v27, -v29, v27, v26
	v_cmp_lt_f32_e64 s[0:1], 0, v27
	s_nop 1
	v_cndmask_b32_e64 v27, v28, v29, s[0:1]
	v_mul_f32_e32 v28, 0x37800000, v27
	v_cndmask_b32_e32 v27, v27, v28, vcc
	v_cmp_class_f32_e32 vcc, v26, v171
	s_nop 1
	v_cndmask_b32_e32 v26, v27, v26, vcc
	v_div_scale_f32 v27, s[0:1], v26, v26, 1.0
	v_rcp_f32_e32 v28, v27
	s_nop 0
	v_fma_f32 v29, -v27, v28, 1.0
	v_fmac_f32_e32 v28, v29, v28
	v_div_scale_f32 v29, vcc, 1.0, v26, 1.0
	v_mul_f32_e32 v30, v29, v28
	v_fma_f32 v31, -v27, v30, v29
	v_fmac_f32_e32 v30, v31, v28
	v_fma_f32 v27, -v27, v30, v29
	v_div_fmas_f32 v27, v27, v28, v30
	v_div_fixup_f32 v26, v27, v26, 1.0
	v_pk_mul_f32 v[24:25], v[26:27], v[24:25] op_sel_hi:[0,1]
	v_pk_mul_f32 v[24:25], v[4:5], v[24:25]
	s_nop 0
	v_cvt_pk_bf16_f32 v26, v24, v25
	v_lshl_add_u64 v[24:25], v[8:9], 0, s[4:5]
	global_store_dword v[24:25], v26, off
	s_and_saveexec_b64 s[0:1], s[2:3]
	s_cbranch_execz .LBB0_808
	v_readlane_b32 s4, v253, 4
	v_readlane_b32 s5, v253, 5
	s_nop 1
	s_waitcnt vmcnt(2)
	v_lshlrev_b32_e32 v24, 16, v42
	v_mul_f32_e32 v26, 0x3cb504f3, v24
	v_lshl_add_u64 v[24:25], v[6:7], 0, s[4:5]
	global_store_dword v[24:25], v26, off
	s_branch .LBB0_808
